# phase-8 paged-cache gather rider: 4 tasks per trip (4 page-table lookups, then 32 row loads, then 32 convert+store steps)
# baseline (speedup 1.0000x reference)
.LBB0_231:
	s_mul_i32 s100, s17, 3
	s_add_i32 s100, s100, s96
	s_cmp_lt_i32 s100, s93
	s_cbranch_scc0 .Lcg_one
	s_mov_b32 s101, s2
	s_ashr_i32 s3, s101, 13
	s_lshl_b32 s18, s3, 6
	s_bfe_u32 s19, s101, 0x60007
	s_or_b32 s18, s18, s19
	s_ashr_i32 s19, s18, 31
	s_and_b32 s20, s101, 0x1ffe
	s_lshl_b64 s[18:19], s[18:19], 2
	s_add_u32 s18, s12, s18
	s_addc_u32 s19, s13, s19
	global_load_dword v72, v145, s[18:19]
	s_mul_i32 s101, s91, 1
	s_add_i32 s101, s101, s2
	s_ashr_i32 s3, s101, 13
	s_lshl_b32 s18, s3, 6
	s_bfe_u32 s19, s101, 0x60007
	s_or_b32 s18, s18, s19
	s_ashr_i32 s19, s18, 31
	s_and_b32 s20, s101, 0x1ffe
	s_lshl_b64 s[18:19], s[18:19], 2
	s_add_u32 s18, s12, s18
	s_addc_u32 s19, s13, s19
	global_load_dword v8, v145, s[18:19]
	s_mul_i32 s101, s91, 2
	s_add_i32 s101, s101, s2
	s_ashr_i32 s3, s101, 13
	s_lshl_b32 s18, s3, 6
	s_bfe_u32 s19, s101, 0x60007
	s_or_b32 s18, s18, s19
	s_ashr_i32 s19, s18, 31
	s_and_b32 s20, s101, 0x1ffe
	s_lshl_b64 s[18:19], s[18:19], 2
	s_add_u32 s18, s12, s18
	s_addc_u32 s19, s13, s19
	global_load_dword v44, v145, s[18:19]
	s_mul_i32 s101, s91, 3
	s_add_i32 s101, s101, s2
	s_ashr_i32 s3, s101, 13
	s_lshl_b32 s18, s3, 6
	s_bfe_u32 s19, s101, 0x60007
	s_or_b32 s18, s18, s19
	s_ashr_i32 s19, s18, 31
	s_and_b32 s20, s101, 0x1ffe
	s_lshl_b64 s[18:19], s[18:19], 2
	s_add_u32 s18, s12, s18
	s_addc_u32 s19, s13, s19
	global_load_dword v116, v145, s[18:19]
	v_mov_b32_e32 v7, v145
	s_waitcnt vmcnt(0)
	s_mov_b32 s101, s2
	s_ashr_i32 s3, s101, 13
	s_lshl_b32 s18, s3, 6
	s_bfe_u32 s19, s101, 0x60007
	s_or_b32 s18, s18, s19
	s_ashr_i32 s19, s18, 31
	s_and_b32 s20, s101, 0x1ffe
	s_lshl_b64 s[18:19], s[18:19], 2
	s_add_u32 s18, s12, s18
	s_addc_u32 s19, s13, s19
	s_lshl_b32 s18, s101, 12
	s_and_b32 s40, s18, 0x7e000
	s_or_b32 s18, s20, 1
	s_lshl_b32 s19, s18, 12
	s_lshl_b32 s3, s3, 2
	v_ashrrev_i32_e32 v73, 31, v72
	v_lshlrev_b64 v[72:73], 19, v[72:73]
	v_lshl_add_u64 v[88:89], v[4:5], 0, v[72:73]
	v_lshl_add_u64 v[84:85], v[88:89], 0, s[40:41]
	global_load_dwordx4 v[72:75], v[84:85], off nt
	global_load_dwordx4 v[76:79], v[84:85], off offset:1024 nt
	global_load_dwordx4 v[80:83], v[84:85], off offset:2048 nt
	s_nop 0
	global_load_dwordx4 v[84:87], v[84:85], off offset:3072 nt
	s_and_b32 s40, s19, 0x7f000
	v_lshl_add_u64 v[100:101], v[88:89], 0, s[40:41]
	global_load_dwordx4 v[88:91], v[100:101], off nt
	global_load_dwordx4 v[92:95], v[100:101], off offset:1024 nt
	global_load_dwordx4 v[96:99], v[100:101], off offset:2048 nt
	s_nop 0
	global_load_dwordx4 v[100:103], v[100:101], off offset:3072 nt
	s_mul_i32 s101, s91, 1
	s_add_i32 s101, s101, s2
	s_ashr_i32 s3, s101, 13
	s_lshl_b32 s18, s3, 6
	s_bfe_u32 s19, s101, 0x60007
	s_or_b32 s18, s18, s19
	s_ashr_i32 s19, s18, 31
	s_and_b32 s20, s101, 0x1ffe
	s_lshl_b64 s[18:19], s[18:19], 2
	s_add_u32 s18, s12, s18
	s_addc_u32 s19, s13, s19
	s_lshl_b32 s18, s101, 12
	s_and_b32 s40, s18, 0x7e000
	s_or_b32 s18, s20, 1
	s_lshl_b32 s19, s18, 12
	s_lshl_b32 s3, s3, 2
	v_ashrrev_i32_e32 v9, 31, v8
	v_lshlrev_b64 v[8:9], 19, v[8:9]
	v_lshl_add_u64 v[24:25], v[4:5], 0, v[8:9]
	v_lshl_add_u64 v[20:21], v[24:25], 0, s[40:41]
	global_load_dwordx4 v[8:11], v[20:21], off nt
	global_load_dwordx4 v[12:15], v[20:21], off offset:1024 nt
	global_load_dwordx4 v[16:19], v[20:21], off offset:2048 nt
	s_nop 0
	global_load_dwordx4 v[20:23], v[20:21], off offset:3072 nt
	s_and_b32 s40, s19, 0x7f000
	v_lshl_add_u64 v[36:37], v[24:25], 0, s[40:41]
	global_load_dwordx4 v[24:27], v[36:37], off nt
	global_load_dwordx4 v[28:31], v[36:37], off offset:1024 nt
	global_load_dwordx4 v[32:35], v[36:37], off offset:2048 nt
	s_nop 0
	global_load_dwordx4 v[36:39], v[36:37], off offset:3072 nt
	s_mul_i32 s101, s91, 2
	s_add_i32 s101, s101, s2
	s_ashr_i32 s3, s101, 13
	s_lshl_b32 s18, s3, 6
	s_bfe_u32 s19, s101, 0x60007
	s_or_b32 s18, s18, s19
	s_ashr_i32 s19, s18, 31
	s_and_b32 s20, s101, 0x1ffe
	s_lshl_b64 s[18:19], s[18:19], 2
	s_add_u32 s18, s12, s18
	s_addc_u32 s19, s13, s19
	s_lshl_b32 s18, s101, 12
	s_and_b32 s40, s18, 0x7e000
	s_or_b32 s18, s20, 1
	s_lshl_b32 s19, s18, 12
	s_lshl_b32 s3, s3, 2
	v_ashrrev_i32_e32 v45, 31, v44
	v_lshlrev_b64 v[44:45], 19, v[44:45]
	v_lshl_add_u64 v[60:61], v[4:5], 0, v[44:45]
	v_lshl_add_u64 v[56:57], v[60:61], 0, s[40:41]
	global_load_dwordx4 v[44:47], v[56:57], off nt
	global_load_dwordx4 v[48:51], v[56:57], off offset:1024 nt
	global_load_dwordx4 v[52:55], v[56:57], off offset:2048 nt
	s_nop 0
	global_load_dwordx4 v[56:59], v[56:57], off offset:3072 nt
	s_and_b32 s40, s19, 0x7f000
	v_lshl_add_u64 v[108:109], v[60:61], 0, s[40:41]
	global_load_dwordx4 v[60:63], v[108:109], off nt
	global_load_dwordx4 v[64:67], v[108:109], off offset:1024 nt
	global_load_dwordx4 v[68:71], v[108:109], off offset:2048 nt
	s_nop 0
	global_load_dwordx4 v[108:111], v[108:109], off offset:3072 nt
	s_mul_i32 s101, s91, 3
	s_add_i32 s101, s101, s2
	s_ashr_i32 s3, s101, 13
	s_lshl_b32 s18, s3, 6
	s_bfe_u32 s19, s101, 0x60007
	s_or_b32 s18, s18, s19
	s_ashr_i32 s19, s18, 31
	s_and_b32 s20, s101, 0x1ffe
	s_lshl_b64 s[18:19], s[18:19], 2
	s_add_u32 s18, s12, s18
	s_addc_u32 s19, s13, s19
	s_lshl_b32 s18, s101, 12
	s_and_b32 s40, s18, 0x7e000
	s_or_b32 s18, s20, 1
	s_lshl_b32 s19, s18, 12
	s_lshl_b32 s3, s3, 2
	v_ashrrev_i32_e32 v117, 31, v116
	v_lshlrev_b64 v[116:117], 19, v[116:117]
	v_lshl_add_u64 v[132:133], v[4:5], 0, v[116:117]
	v_lshl_add_u64 v[128:129], v[132:133], 0, s[40:41]
	global_load_dwordx4 v[116:119], v[128:129], off nt
	global_load_dwordx4 v[120:123], v[128:129], off offset:1024 nt
	global_load_dwordx4 v[124:127], v[128:129], off offset:2048 nt
	s_nop 0
	global_load_dwordx4 v[128:131], v[128:129], off offset:3072 nt
	s_and_b32 s40, s19, 0x7f000
	v_lshl_add_u64 v[204:205], v[132:133], 0, s[40:41]
	global_load_dwordx4 v[132:135], v[204:205], off nt
	global_load_dwordx4 v[136:139], v[204:205], off offset:1024 nt
	global_load_dwordx4 v[140:143], v[204:205], off offset:2048 nt
	s_nop 0
	global_load_dwordx4 v[204:207], v[204:205], off offset:3072 nt
	s_mov_b32 s101, s2
	s_ashr_i32 s3, s101, 13
	s_lshl_b32 s18, s3, 6
	s_bfe_u32 s19, s101, 0x60007
	s_or_b32 s18, s18, s19
	s_ashr_i32 s19, s18, 31
	s_and_b32 s20, s101, 0x1ffe
	s_lshl_b64 s[18:19], s[18:19], 2
	s_add_u32 s18, s12, s18
	s_addc_u32 s19, s13, s19
	s_lshl_b32 s18, s101, 12
	s_and_b32 s40, s18, 0x7e000
	s_or_b32 s18, s20, 1
	s_lshl_b32 s19, s18, 12
	s_lshl_b32 s3, s3, 2
	s_lshl_b32 s40, s20, 8
	s_waitcnt vmcnt(31)
	v_cvt_pk_bf16_f32 v72, v72, v73
	v_cvt_pk_bf16_f32 v73, v74, v75
	v_or_b32_e32 v74, s3, v3
	v_ashrrev_i32_e32 v75, 31, v74
	v_lshlrev_b64 v[104:105], 21, v[74:75]
	v_or_b32_e32 v74, 2, v74
	v_lshl_add_u64 v[104:105], s[4:5], 0, v[104:105]
	v_ashrrev_i32_e32 v75, 31, v74
	v_lshl_add_u64 v[106:107], v[104:105], 0, s[40:41]
	v_lshlrev_b64 v[74:75], 21, v[74:75]
	v_lshl_add_u64 v[106:107], v[106:107], 0, v[6:7]
	v_lshl_add_u64 v[74:75], s[4:5], 0, v[74:75]
	global_store_dwordx2 v[106:107], v[72:73], off
	s_waitcnt vmcnt(31)
	v_cvt_pk_bf16_f32 v72, v76, v77
	v_lshl_add_u64 v[76:77], v[74:75], 0, s[40:41]
	v_lshl_add_u64 v[76:77], v[76:77], 0, v[6:7]
	v_cvt_pk_bf16_f32 v73, v78, v79
	global_store_dwordx2 v[76:77], v[72:73], off
	v_add_u32_e32 v76, s3, v149
	v_ashrrev_i32_e32 v77, 31, v76
	v_lshlrev_b64 v[76:77], 21, v[76:77]
	v_lshl_add_u64 v[76:77], s[4:5], 0, v[76:77]
	v_lshl_add_u64 v[78:79], v[76:77], 0, s[40:41]
	v_lshl_add_u64 v[78:79], v[78:79], 0, v[6:7]
	s_waitcnt vmcnt(31)
	v_cvt_pk_bf16_f32 v72, v80, v81
	v_cvt_pk_bf16_f32 v73, v82, v83
	global_store_dwordx2 v[78:79], v[72:73], off
	v_add_u32_e32 v78, s3, v156
	v_ashrrev_i32_e32 v79, 31, v78
	v_lshlrev_b64 v[78:79], 21, v[78:79]
	v_lshl_add_u64 v[78:79], s[4:5], 0, v[78:79]
	v_lshl_add_u64 v[80:81], v[78:79], 0, s[40:41]
	v_lshl_add_u64 v[80:81], v[80:81], 0, v[6:7]
	s_lshl_b32 s40, s18, 8
	s_waitcnt vmcnt(31)
	v_cvt_pk_bf16_f32 v72, v84, v85
	v_cvt_pk_bf16_f32 v73, v86, v87
	global_store_dwordx2 v[80:81], v[72:73], off
	v_lshl_add_u64 v[80:81], v[104:105], 0, s[40:41]
	v_lshl_add_u64 v[74:75], v[74:75], 0, s[40:41]
	s_waitcnt vmcnt(31)
	v_cvt_pk_bf16_f32 v72, v88, v89
	v_cvt_pk_bf16_f32 v73, v90, v91
	v_lshl_add_u64 v[80:81], v[80:81], 0, v[6:7]
	v_lshl_add_u64 v[74:75], v[74:75], 0, v[6:7]
	global_store_dwordx2 v[80:81], v[72:73], off
	s_waitcnt vmcnt(31)
	v_cvt_pk_bf16_f32 v72, v92, v93
	v_cvt_pk_bf16_f32 v73, v94, v95
	global_store_dwordx2 v[74:75], v[72:73], off
	v_lshl_add_u64 v[74:75], v[76:77], 0, s[40:41]
	v_lshl_add_u64 v[74:75], v[74:75], 0, v[6:7]
	s_waitcnt vmcnt(31)
	v_cvt_pk_bf16_f32 v72, v96, v97
	v_cvt_pk_bf16_f32 v73, v98, v99
	global_store_dwordx2 v[74:75], v[72:73], off
	v_lshl_add_u64 v[74:75], v[78:79], 0, s[40:41]
	v_lshl_add_u64 v[74:75], v[74:75], 0, v[6:7]
	s_waitcnt vmcnt(31)
	v_cvt_pk_bf16_f32 v72, v100, v101
	v_cvt_pk_bf16_f32 v73, v102, v103
	global_store_dwordx2 v[74:75], v[72:73], off
	s_mul_i32 s101, s91, 1
	s_add_i32 s101, s101, s2
	s_ashr_i32 s3, s101, 13
	s_lshl_b32 s18, s3, 6
	s_bfe_u32 s19, s101, 0x60007
	s_or_b32 s18, s18, s19
	s_ashr_i32 s19, s18, 31
	s_and_b32 s20, s101, 0x1ffe
	s_lshl_b64 s[18:19], s[18:19], 2
	s_add_u32 s18, s12, s18
	s_addc_u32 s19, s13, s19
	s_lshl_b32 s18, s101, 12
	s_and_b32 s40, s18, 0x7e000
	s_or_b32 s18, s20, 1
	s_lshl_b32 s19, s18, 12
	s_lshl_b32 s3, s3, 2
	s_lshl_b32 s40, s20, 8
	s_waitcnt vmcnt(31)
	v_cvt_pk_bf16_f32 v8, v8, v9
	v_cvt_pk_bf16_f32 v9, v10, v11
	v_or_b32_e32 v10, s3, v3
	v_ashrrev_i32_e32 v11, 31, v10
	v_lshlrev_b64 v[40:41], 21, v[10:11]
	v_or_b32_e32 v10, 2, v10
	v_lshl_add_u64 v[40:41], s[4:5], 0, v[40:41]
	v_ashrrev_i32_e32 v11, 31, v10
	v_lshl_add_u64 v[42:43], v[40:41], 0, s[40:41]
	v_lshlrev_b64 v[10:11], 21, v[10:11]
	v_lshl_add_u64 v[42:43], v[42:43], 0, v[6:7]
	v_lshl_add_u64 v[10:11], s[4:5], 0, v[10:11]
	global_store_dwordx2 v[42:43], v[8:9], off
	s_waitcnt vmcnt(31)
	v_cvt_pk_bf16_f32 v8, v12, v13
	v_lshl_add_u64 v[12:13], v[10:11], 0, s[40:41]
	v_lshl_add_u64 v[12:13], v[12:13], 0, v[6:7]
	v_cvt_pk_bf16_f32 v9, v14, v15
	global_store_dwordx2 v[12:13], v[8:9], off
	v_add_u32_e32 v12, s3, v149
	v_ashrrev_i32_e32 v13, 31, v12
	v_lshlrev_b64 v[12:13], 21, v[12:13]
	v_lshl_add_u64 v[12:13], s[4:5], 0, v[12:13]
	v_lshl_add_u64 v[14:15], v[12:13], 0, s[40:41]
	v_lshl_add_u64 v[14:15], v[14:15], 0, v[6:7]
	s_waitcnt vmcnt(31)
	v_cvt_pk_bf16_f32 v8, v16, v17
	v_cvt_pk_bf16_f32 v9, v18, v19
	global_store_dwordx2 v[14:15], v[8:9], off
	v_add_u32_e32 v14, s3, v156
	v_ashrrev_i32_e32 v15, 31, v14
	v_lshlrev_b64 v[14:15], 21, v[14:15]
	v_lshl_add_u64 v[14:15], s[4:5], 0, v[14:15]
	v_lshl_add_u64 v[16:17], v[14:15], 0, s[40:41]
	v_lshl_add_u64 v[16:17], v[16:17], 0, v[6:7]
	s_lshl_b32 s40, s18, 8
	s_waitcnt vmcnt(31)
	v_cvt_pk_bf16_f32 v8, v20, v21
	v_cvt_pk_bf16_f32 v9, v22, v23
	global_store_dwordx2 v[16:17], v[8:9], off
	v_lshl_add_u64 v[16:17], v[40:41], 0, s[40:41]
	v_lshl_add_u64 v[10:11], v[10:11], 0, s[40:41]
	s_waitcnt vmcnt(31)
	v_cvt_pk_bf16_f32 v8, v24, v25
	v_cvt_pk_bf16_f32 v9, v26, v27
	v_lshl_add_u64 v[16:17], v[16:17], 0, v[6:7]
	v_lshl_add_u64 v[10:11], v[10:11], 0, v[6:7]
	global_store_dwordx2 v[16:17], v[8:9], off
	s_waitcnt vmcnt(31)
	v_cvt_pk_bf16_f32 v8, v28, v29
	v_cvt_pk_bf16_f32 v9, v30, v31
	global_store_dwordx2 v[10:11], v[8:9], off
	v_lshl_add_u64 v[10:11], v[12:13], 0, s[40:41]
	v_lshl_add_u64 v[10:11], v[10:11], 0, v[6:7]
	s_waitcnt vmcnt(31)
	v_cvt_pk_bf16_f32 v8, v32, v33
	v_cvt_pk_bf16_f32 v9, v34, v35
	global_store_dwordx2 v[10:11], v[8:9], off
	v_lshl_add_u64 v[10:11], v[14:15], 0, s[40:41]
	v_lshl_add_u64 v[10:11], v[10:11], 0, v[6:7]
	s_waitcnt vmcnt(31)
	v_cvt_pk_bf16_f32 v8, v36, v37
	v_cvt_pk_bf16_f32 v9, v38, v39
	global_store_dwordx2 v[10:11], v[8:9], off
	s_mul_i32 s101, s91, 2
	s_add_i32 s101, s101, s2
	s_ashr_i32 s3, s101, 13
	s_lshl_b32 s18, s3, 6
	s_bfe_u32 s19, s101, 0x60007
	s_or_b32 s18, s18, s19
	s_ashr_i32 s19, s18, 31
	s_and_b32 s20, s101, 0x1ffe
	s_lshl_b64 s[18:19], s[18:19], 2
	s_add_u32 s18, s12, s18
	s_addc_u32 s19, s13, s19
	s_lshl_b32 s18, s101, 12
	s_and_b32 s40, s18, 0x7e000
	s_or_b32 s18, s20, 1
	s_lshl_b32 s19, s18, 12
	s_lshl_b32 s3, s3, 2
	s_lshl_b32 s40, s20, 8
	s_waitcnt vmcnt(31)
	v_cvt_pk_bf16_f32 v44, v44, v45
	v_cvt_pk_bf16_f32 v45, v46, v47
	v_or_b32_e32 v46, s3, v3
	v_ashrrev_i32_e32 v47, 31, v46
	v_lshlrev_b64 v[112:113], 21, v[46:47]
	v_or_b32_e32 v46, 2, v46
	v_lshl_add_u64 v[112:113], s[4:5], 0, v[112:113]
	v_ashrrev_i32_e32 v47, 31, v46
	v_lshl_add_u64 v[114:115], v[112:113], 0, s[40:41]
	v_lshlrev_b64 v[46:47], 21, v[46:47]
	v_lshl_add_u64 v[114:115], v[114:115], 0, v[6:7]
	v_lshl_add_u64 v[46:47], s[4:5], 0, v[46:47]
	global_store_dwordx2 v[114:115], v[44:45], off
	s_waitcnt vmcnt(31)
	v_cvt_pk_bf16_f32 v44, v48, v49
	v_lshl_add_u64 v[48:49], v[46:47], 0, s[40:41]
	v_lshl_add_u64 v[48:49], v[48:49], 0, v[6:7]
	v_cvt_pk_bf16_f32 v45, v50, v51
	global_store_dwordx2 v[48:49], v[44:45], off
	v_add_u32_e32 v48, s3, v149
	v_ashrrev_i32_e32 v49, 31, v48
	v_lshlrev_b64 v[48:49], 21, v[48:49]
	v_lshl_add_u64 v[48:49], s[4:5], 0, v[48:49]
	v_lshl_add_u64 v[50:51], v[48:49], 0, s[40:41]
	v_lshl_add_u64 v[50:51], v[50:51], 0, v[6:7]
	s_waitcnt vmcnt(31)
	v_cvt_pk_bf16_f32 v44, v52, v53
	v_cvt_pk_bf16_f32 v45, v54, v55
	global_store_dwordx2 v[50:51], v[44:45], off
	v_add_u32_e32 v50, s3, v156
	v_ashrrev_i32_e32 v51, 31, v50
	v_lshlrev_b64 v[50:51], 21, v[50:51]
	v_lshl_add_u64 v[50:51], s[4:5], 0, v[50:51]
	v_lshl_add_u64 v[52:53], v[50:51], 0, s[40:41]
	v_lshl_add_u64 v[52:53], v[52:53], 0, v[6:7]
	s_lshl_b32 s40, s18, 8
	s_waitcnt vmcnt(31)
	v_cvt_pk_bf16_f32 v44, v56, v57
	v_cvt_pk_bf16_f32 v45, v58, v59
	global_store_dwordx2 v[52:53], v[44:45], off
	v_lshl_add_u64 v[52:53], v[112:113], 0, s[40:41]
	v_lshl_add_u64 v[46:47], v[46:47], 0, s[40:41]
	s_waitcnt vmcnt(31)
	v_cvt_pk_bf16_f32 v44, v60, v61
	v_cvt_pk_bf16_f32 v45, v62, v63
	v_lshl_add_u64 v[52:53], v[52:53], 0, v[6:7]
	v_lshl_add_u64 v[46:47], v[46:47], 0, v[6:7]
	global_store_dwordx2 v[52:53], v[44:45], off
	s_waitcnt vmcnt(31)
	v_cvt_pk_bf16_f32 v44, v64, v65
	v_cvt_pk_bf16_f32 v45, v66, v67
	global_store_dwordx2 v[46:47], v[44:45], off
	v_lshl_add_u64 v[46:47], v[48:49], 0, s[40:41]
	v_lshl_add_u64 v[46:47], v[46:47], 0, v[6:7]
	s_waitcnt vmcnt(31)
	v_cvt_pk_bf16_f32 v44, v68, v69
	v_cvt_pk_bf16_f32 v45, v70, v71
	global_store_dwordx2 v[46:47], v[44:45], off
	v_lshl_add_u64 v[46:47], v[50:51], 0, s[40:41]
	v_lshl_add_u64 v[46:47], v[46:47], 0, v[6:7]
	s_waitcnt vmcnt(31)
	v_cvt_pk_bf16_f32 v44, v108, v109
	v_cvt_pk_bf16_f32 v45, v110, v111
	global_store_dwordx2 v[46:47], v[44:45], off
	s_mul_i32 s101, s91, 3
	s_add_i32 s101, s101, s2
	s_ashr_i32 s3, s101, 13
	s_lshl_b32 s18, s3, 6
	s_bfe_u32 s19, s101, 0x60007
	s_or_b32 s18, s18, s19
	s_ashr_i32 s19, s18, 31
	s_and_b32 s20, s101, 0x1ffe
	s_lshl_b64 s[18:19], s[18:19], 2
	s_add_u32 s18, s12, s18
	s_addc_u32 s19, s13, s19
	s_lshl_b32 s18, s101, 12
	s_and_b32 s40, s18, 0x7e000
	s_or_b32 s18, s20, 1
	s_lshl_b32 s19, s18, 12
	s_lshl_b32 s3, s3, 2
	s_lshl_b32 s40, s20, 8
	s_waitcnt vmcnt(31)
	v_cvt_pk_bf16_f32 v116, v116, v117
	v_cvt_pk_bf16_f32 v117, v118, v119
	v_or_b32_e32 v118, s3, v3
	v_ashrrev_i32_e32 v119, 31, v118
	v_lshlrev_b64 v[208:209], 21, v[118:119]
	v_or_b32_e32 v118, 2, v118
	v_lshl_add_u64 v[208:209], s[4:5], 0, v[208:209]
	v_ashrrev_i32_e32 v119, 31, v118
	v_lshl_add_u64 v[210:211], v[208:209], 0, s[40:41]
	v_lshlrev_b64 v[118:119], 21, v[118:119]
	v_lshl_add_u64 v[210:211], v[210:211], 0, v[6:7]
	v_lshl_add_u64 v[118:119], s[4:5], 0, v[118:119]
	global_store_dwordx2 v[210:211], v[116:117], off
	s_waitcnt vmcnt(31)
	v_cvt_pk_bf16_f32 v116, v120, v121
	v_lshl_add_u64 v[120:121], v[118:119], 0, s[40:41]
	v_lshl_add_u64 v[120:121], v[120:121], 0, v[6:7]
	v_cvt_pk_bf16_f32 v117, v122, v123
	global_store_dwordx2 v[120:121], v[116:117], off
	v_add_u32_e32 v120, s3, v149
	v_ashrrev_i32_e32 v121, 31, v120
	v_lshlrev_b64 v[120:121], 21, v[120:121]
	v_lshl_add_u64 v[120:121], s[4:5], 0, v[120:121]
	v_lshl_add_u64 v[122:123], v[120:121], 0, s[40:41]
	v_lshl_add_u64 v[122:123], v[122:123], 0, v[6:7]
	s_waitcnt vmcnt(31)
	v_cvt_pk_bf16_f32 v116, v124, v125
	v_cvt_pk_bf16_f32 v117, v126, v127
	global_store_dwordx2 v[122:123], v[116:117], off
	v_add_u32_e32 v122, s3, v156
	v_ashrrev_i32_e32 v123, 31, v122
	v_lshlrev_b64 v[122:123], 21, v[122:123]
	v_lshl_add_u64 v[122:123], s[4:5], 0, v[122:123]
	v_lshl_add_u64 v[124:125], v[122:123], 0, s[40:41]
	v_lshl_add_u64 v[124:125], v[124:125], 0, v[6:7]
	s_lshl_b32 s40, s18, 8
	s_waitcnt vmcnt(31)
	v_cvt_pk_bf16_f32 v116, v128, v129
	v_cvt_pk_bf16_f32 v117, v130, v131
	global_store_dwordx2 v[124:125], v[116:117], off
	v_lshl_add_u64 v[124:125], v[208:209], 0, s[40:41]
	v_lshl_add_u64 v[118:119], v[118:119], 0, s[40:41]
	s_waitcnt vmcnt(31)
	v_cvt_pk_bf16_f32 v116, v132, v133
	v_cvt_pk_bf16_f32 v117, v134, v135
	v_lshl_add_u64 v[124:125], v[124:125], 0, v[6:7]
	v_lshl_add_u64 v[118:119], v[118:119], 0, v[6:7]
	global_store_dwordx2 v[124:125], v[116:117], off
	s_waitcnt vmcnt(31)
	v_cvt_pk_bf16_f32 v116, v136, v137
	v_cvt_pk_bf16_f32 v117, v138, v139
	global_store_dwordx2 v[118:119], v[116:117], off
	v_lshl_add_u64 v[118:119], v[120:121], 0, s[40:41]
	v_lshl_add_u64 v[118:119], v[118:119], 0, v[6:7]
	s_waitcnt vmcnt(31)
	v_cvt_pk_bf16_f32 v116, v140, v141
	v_cvt_pk_bf16_f32 v117, v142, v143
	global_store_dwordx2 v[118:119], v[116:117], off
	v_lshl_add_u64 v[118:119], v[122:123], 0, s[40:41]
	v_lshl_add_u64 v[118:119], v[118:119], 0, v[6:7]
	s_waitcnt vmcnt(31)
	v_cvt_pk_bf16_f32 v116, v204, v205
	v_cvt_pk_bf16_f32 v117, v206, v207
	global_store_dwordx2 v[118:119], v[116:117], off
	s_lshl_b32 s100, s17, 2
	s_add_i32 s96, s96, s100
	s_lshl_b32 s100, s91, 2
	s_add_i32 s2, s2, s100
	s_cmp_ge_i32 s96, s93
	s_cbranch_scc0 .LBB0_231
	s_branch .LBB0_179
